# SB softplus: removed dead denormal/inf handling of logf(1+exp(-|z|)) expansions (arg in [1,2], bit-exact), on top of interleaved GEMM loops
# speedup vs baseline: 1.0340x; 1.0030x over previous
.LBB0_474:
	global_load_dwordx4 v[80:83], v213, s[38:39]
	global_load_dwordx4 v[132:135], v213, s[38:39] offset:32
	global_load_dwordx4 v[128:131], v213, s[38:39] offset:64
	ds_read_b128 v[64:67], v220 offset:8192
	ds_read_b128 v[84:87], v221 offset:8192
	global_load_dwordx4 v[140:143], v213, s[38:39] offset:96
	global_load_dwordx4 v[136:139], v213, s[38:39] offset:128
	v_add_u32_e32 v171, v214, v158
	v_add_u32_e32 v159, 64, v171
	s_waitcnt vmcnt(0) lgkmcnt(0)
	v_mfma_f32_32x32x16_bf16 v[64:79], v[64:67], v[80:83], 0
	v_mfma_f32_32x32x16_bf16 v[64:79], v[84:87], v[132:135], v[64:79]
	ds_read_b128 v[84:87], v222 offset:8192
	ds_read_b128 v[120:123], v223 offset:8192
	global_load_dwordx4 v[144:147], v213, s[38:39] offset:160
	global_load_dwordx4 v[148:151], v213, s[38:39] offset:192
	global_load_dwordx4 v[124:127], v213, s[38:39] offset:224
	s_waitcnt lgkmcnt(1)
	v_mfma_f32_32x32x16_bf16 v[64:79], v[84:87], v[128:131], v[64:79]
	ds_read_b128 v[84:87], v224 offset:8192
	s_waitcnt lgkmcnt(1)
	v_mfma_f32_32x32x16_bf16 v[64:79], v[120:123], v[140:143], v[64:79]
	ds_read_b128 v[120:123], v225 offset:8192
	s_waitcnt lgkmcnt(1)
	v_mfma_f32_32x32x16_bf16 v[64:79], v[84:87], v[136:139], v[64:79]
	s_waitcnt vmcnt(2) lgkmcnt(0)
	v_mfma_f32_32x32x16_bf16 v[64:79], v[120:123], v[144:147], v[64:79]
	ds_read_b128 v[84:87], v226 offset:8192
	ds_read_b128 v[120:123], v227 offset:8192
	s_waitcnt vmcnt(1) lgkmcnt(1)
	v_mfma_f32_32x32x16_bf16 v[64:79], v[84:87], v[148:151], v[64:79]
	s_waitcnt vmcnt(0) lgkmcnt(0)
	v_mfma_f32_32x32x16_bf16 v[64:79], v[120:123], v[124:127], v[64:79]
	s_nop 11
	v_mul_f32_e32 v84, 0x3db504f3, v64
	v_mul_f32_e32 v85, 0x3db504f3, v65
	v_max_f32_e32 v184, 0, v84
	v_mul_f32_e64 v84, |v84|, s68
	v_mul_f32_e32 v86, 0x3db504f3, v66
	v_max_f32_e32 v182, 0, v85
	v_mul_f32_e64 v85, |v85|, s68
	v_exp_f32_e32 v84, v84
	v_mul_f32_e32 v87, 0x3db504f3, v67
	v_max_f32_e32 v180, 0, v86
	v_mul_f32_e64 v86, |v86|, s68
	v_exp_f32_e32 v85, v85
	v_mul_f32_e32 v120, 0x3db504f3, v68
	v_max_f32_e32 v178, 0, v87
	v_mul_f32_e64 v87, |v87|, s68
	v_exp_f32_e32 v86, v86
	v_mul_f32_e32 v121, 0x3db504f3, v69
	v_mul_f32_e32 v123, 0x3db504f3, v71
	v_mul_f32_e64 v175, |v120|, s68
	v_exp_f32_e32 v87, v87
	v_mul_f32_e32 v122, 0x3db504f3, v70
	v_max_f32_e32 v176, 0, v120
	v_max_f32_e32 v174, 0, v121
	v_mul_f32_e64 v121, |v121|, s68
	v_max_f32_e32 v120, 0, v123
	v_mul_f32_e64 v123, |v123|, s68
	v_exp_f32_e32 v175, v175
	v_add_f32_e32 v84, 1.0, v84
	v_max_f32_e32 v172, 0, v122
	v_mul_f32_e64 v122, |v122|, s68
	v_exp_f32_e32 v121, v121
	v_exp_f32_e32 v123, v123
	v_add_f32_e32 v85, 1.0, v85
	v_exp_f32_e32 v122, v122
	v_add_f32_e32 v86, 1.0, v86
	v_add_f32_e32 v87, 1.0, v87
	v_add_f32_e32 v175, 1.0, v175
	v_log_f32_e32 v84, v84
	v_add_f32_e32 v121, 1.0, v121
	v_add_f32_e32 v123, 1.0, v123
	v_log_f32_e32 v85, v85
	v_add_f32_e32 v122, 1.0, v122
	v_log_f32_e32 v86, v86
	v_log_f32_e32 v87, v87
	v_log_f32_e32 v175, v175
	v_mul_f32_e32 v189, 0x3f317217, v84
	v_log_f32_e32 v121, v121
	v_mul_f32_e32 v190, 0x3f317217, v85
	v_fma_f32 v189, v84, s70, -v189
	v_log_f32_e32 v122, v122
	v_mul_f32_e32 v191, 0x3f317217, v86
	v_fma_f32 v190, v85, s70, -v190
	v_fmac_f32_e32 v189, 0x3377d1cf, v84
	v_log_f32_e32 v123, v123
	v_mul_f32_e32 v192, 0x3f317217, v87
	v_fma_f32 v191, v86, s70, -v191
	v_fmac_f32_e32 v190, 0x3377d1cf, v85
	v_fmac_f32_e32 v189, 0x3f317217, v84
	v_mul_f32_e32 v173, 0x3db504f3, v72
	v_mul_f32_e32 v193, 0x3f317217, v175
	v_fma_f32 v192, v87, s70, -v192
	v_fmac_f32_e32 v191, 0x3377d1cf, v86
	v_fmac_f32_e32 v190, 0x3f317217, v85
	v_mov_b32_e32 v84, v189
	v_mul_f32_e64 v177, |v173|, s68
	v_mul_f32_e32 v194, 0x3f317217, v121
	v_fma_f32 v193, v175, s70, -v193
	v_fmac_f32_e32 v192, 0x3377d1cf, v87
	v_fmac_f32_e32 v191, 0x3f317217, v86
	v_mov_b32_e32 v85, v190
	v_exp_f32_e32 v177, v177
	v_mul_f32_e32 v195, 0x3f317217, v122
	v_fma_f32 v194, v121, s70, -v194
	v_fmac_f32_e32 v193, 0x3377d1cf, v175
	v_fmac_f32_e32 v192, 0x3f317217, v87
	v_mov_b32_e32 v86, v191
	v_mul_f32_e32 v196, 0x3f317217, v123
	v_fma_f32 v195, v122, s70, -v195
	v_fmac_f32_e32 v194, 0x3377d1cf, v121
	v_fmac_f32_e32 v193, 0x3f317217, v175
	v_mov_b32_e32 v87, v192
	v_fma_f32 v196, v123, s70, -v196
	v_fmac_f32_e32 v195, 0x3377d1cf, v122
	v_fmac_f32_e32 v194, 0x3f317217, v121
	v_mov_b32_e32 v175, v193
	v_fmac_f32_e32 v196, 0x3377d1cf, v123
	v_fmac_f32_e32 v195, 0x3f317217, v122
	v_mov_b32_e32 v121, v194
	v_fmac_f32_e32 v196, 0x3f317217, v123
	v_mov_b32_e32 v202, v85
	v_mov_b32_e32 v122, v195
	v_add_f32_e32 v85, 1.0, v177
	v_mov_b32_e32 v123, v196
	v_mov_b32_e32 v200, v86
	v_log_f32_e32 v85, v85
	v_mov_b32_e32 v198, v87
	v_max_f32_e32 v86, 0, v173
	v_mul_f32_e32 v87, 0x3f317217, v85
	v_fma_f32 v87, v85, s70, -v87
	v_fmac_f32_e32 v87, 0x3377d1cf, v85
	v_fmac_f32_e32 v87, 0x3f317217, v85
	v_mov_b32_e32 v204, v84
	v_mov_b32_e32 v85, v87
	v_add_f32_e32 v85, v86, v85
	v_mul_f32_e32 v86, 0x3db504f3, v73
	v_mul_f32_e64 v87, |v86|, s68
	v_exp_f32_e32 v87, v87
	v_mov_b32_e32 v190, v122
	v_mov_b32_e32 v188, v123
	v_add_u32_e32 v84, 0x70, v171
	v_cmp_lt_i32_e32 vcc, v84, v154
	v_fma_f32 v72, v72, s67, -v85
	v_max_f32_e32 v86, 0, v86
	v_cndmask_b32_e64 v84, 0, -v85, vcc
	v_add_f32_e32 v85, 1.0, v87
	v_cndmask_b32_e32 v229, v208, v72, vcc
	v_add_u32_e32 v72, 0x71, v171
	v_log_f32_e32 v85, v85
	v_mov_b32_e32 v194, v175
	v_mul_f32_e32 v87, 0x3f317217, v85
	v_fma_f32 v87, v85, s70, -v87
	v_fmac_f32_e32 v87, 0x3377d1cf, v85
	v_fmac_f32_e32 v87, 0x3f317217, v85
	v_mov_b32_e32 v192, v121
	s_nop 0
	v_mov_b32_e32 v85, v87
	v_add_f32_e32 v85, v86, v85
	v_mul_f32_e32 v86, 0x3db504f3, v74
	v_mul_f32_e64 v87, |v86|, s68
	v_exp_f32_e32 v87, v87
	v_cmp_lt_i32_e32 vcc, v72, v154
	v_fma_f32 v72, v73, s67, -v85
	v_add_f32_e32 v73, 1.0, v87
	v_cndmask_b32_e64 v230, 0, -v85, vcc
	v_cndmask_b32_e32 v231, v208, v72, vcc
	v_log_f32_e32 v73, v73
	v_max_f32_e32 v85, 0, v86
	v_add_u32_e32 v72, 0x72, v171
	v_add_f32_e32 v206, v84, v230
	v_mul_f32_e32 v86, 0x3f317217, v73
	v_fma_f32 v86, v73, s70, -v86
	v_fmac_f32_e32 v86, 0x3377d1cf, v73
	v_fmac_f32_e32 v86, 0x3f317217, v73
	s_nop 1
	v_mov_b32_e32 v73, v86
	v_add_f32_e32 v73, v85, v73
	v_mul_f32_e32 v85, 0x3db504f3, v75
	v_mul_f32_e64 v86, |v85|, s68
	v_exp_f32_e32 v86, v86
	v_cmp_lt_i32_e32 vcc, v72, v154
	v_fma_f32 v72, v74, s67, -v73
	s_nop 0
	v_cndmask_b32_e64 v232, 0, -v73, vcc
	v_add_f32_e32 v73, 1.0, v86
	v_cndmask_b32_e32 v233, v208, v72, vcc
	v_add_u32_e32 v72, 0x73, v171
	v_log_f32_e32 v73, v73
	v_max_f32_e32 v74, 0, v85
	v_mul_f32_e32 v85, 0x3f317217, v73
	v_fma_f32 v85, v73, s70, -v85
	v_fmac_f32_e32 v85, 0x3377d1cf, v73
	v_fmac_f32_e32 v85, 0x3f317217, v73
	s_nop 1
	v_mov_b32_e32 v73, v85
	v_add_f32_e32 v73, v74, v73
	v_mul_f32_e32 v74, 0x3db504f3, v76
	v_mul_f32_e64 v85, |v74|, s68
	v_exp_f32_e32 v85, v85
	v_cmp_lt_i32_e32 vcc, v72, v154
	v_fma_f32 v72, v75, s67, -v73
	v_max_f32_e32 v74, 0, v74
	v_cndmask_b32_e64 v234, 0, -v73, vcc
	v_add_f32_e32 v73, 1.0, v85
	v_cndmask_b32_e32 v235, v208, v72, vcc
	v_add_u32_e32 v72, 0x78, v171
	v_log_f32_e32 v73, v73
	v_add_f32_e32 v186, v232, v234
	v_mul_f32_e32 v75, 0x3f317217, v73
	v_fma_f32 v75, v73, s70, -v75
	v_fmac_f32_e32 v75, 0x3377d1cf, v73
	v_fmac_f32_e32 v75, 0x3f317217, v73
	s_nop 1
	v_mov_b32_e32 v73, v75
	v_add_f32_e32 v73, v74, v73
	v_mul_f32_e32 v74, 0x3db504f3, v77
	v_mul_f32_e64 v75, |v74|, s68
	v_exp_f32_e32 v75, v75
	v_cmp_lt_i32_e32 vcc, v72, v154
	v_max_f32_e32 v74, 0, v74
	v_add_f32_e32 v75, 1.0, v75
	v_cndmask_b32_e64 v72, 0, -v73, vcc
	v_fma_f32 v73, v76, s67, -v73
	v_log_f32_e32 v75, v75
	v_cndmask_b32_e32 v73, v208, v73, vcc
	v_add_u32_e32 v76, 0x79, v171
	v_mul_f32_e32 v85, 0x3f317217, v75
	v_fma_f32 v85, v75, s70, -v85
	v_fmac_f32_e32 v85, 0x3377d1cf, v75
	v_fmac_f32_e32 v85, 0x3f317217, v75
	s_nop 1
	v_mov_b32_e32 v75, v85
	v_add_f32_e32 v74, v74, v75
	v_mul_f32_e32 v75, 0x3db504f3, v78
	v_mul_f32_e64 v85, |v75|, s68
	v_exp_f32_e32 v85, v85
	v_cmp_lt_i32_e32 vcc, v76, v154
	v_max_f32_e32 v75, 0, v75
	s_nop 0
	v_cndmask_b32_e64 v76, 0, -v74, vcc
	v_fma_f32 v74, v77, s67, -v74
	v_add_f32_e32 v77, 1.0, v85
	v_cndmask_b32_e32 v74, v208, v74, vcc
	v_add_f32_e32 v72, v72, v76
	v_log_f32_e32 v77, v77
	v_add_u32_e32 v85, 0x7a, v171
	v_mul_f32_e32 v86, 0x3f317217, v77
	v_fma_f32 v86, v77, s70, -v86
	v_fmac_f32_e32 v86, 0x3377d1cf, v77
	v_fmac_f32_e32 v86, 0x3f317217, v77
	s_nop 1
	v_mov_b32_e32 v77, v86
	v_add_f32_e32 v75, v75, v77
	v_mul_f32_e32 v77, 0x3db504f3, v79
	v_mul_f32_e64 v86, |v77|, s68
	v_exp_f32_e32 v86, v86
	v_cmp_lt_i32_e32 vcc, v85, v154
	v_max_f32_e32 v77, 0, v77
	s_nop 0
	v_cndmask_b32_e64 v85, 0, -v75, vcc
	v_fma_f32 v75, v78, s67, -v75
	v_add_f32_e32 v78, 1.0, v86
	v_cndmask_b32_e32 v75, v208, v75, vcc
	s_nop 0
	v_log_f32_e32 v78, v78
	v_add_u32_e32 v86, 0x7b, v171
	v_mul_f32_e32 v87, 0x3f317217, v78
	v_fma_f32 v87, v78, s70, -v87
	v_fmac_f32_e32 v87, 0x3377d1cf, v78
	v_fmac_f32_e32 v87, 0x3f317217, v78
	s_nop 1
	v_mov_b32_e32 v78, v87
	v_add_f32_e32 v77, v77, v78
	v_cmp_lt_i32_e32 vcc, v86, v154
	s_nop 1
	v_cndmask_b32_e64 v78, 0, -v77, vcc
	v_fma_f32 v77, v79, s67, -v77
	v_add_f32_e32 v79, v85, v78
	v_add_f32_e32 v72, v72, v79
	v_mov_b32_e32 v79, v72
	v_mov_b32_e32 v84, v72
	s_nop 1
	v_permlane32_swap_b32_e32 v79, v84
	v_cndmask_b32_e64 v79, v79, v84, s[4:5]
	v_add_f32_e32 v84, 0, v170
	v_cndmask_b32_e64 v86, 0, v79, s[4:5]
	v_add_f32_e32 v84, v84, v86
	v_add_f32_e32 v78, v78, v84
	v_add_f32_e32 v85, v85, v78
	v_cndmask_b32_e32 v77, v208, v77, vcc
	v_add_f32_e32 v76, v76, v85
	v_add_f32_e32 v77, v84, v77
	v_add_f32_e32 v75, v75, v78
	v_add_f32_e32 v74, v74, v85
	v_add_f32_e32 v73, v73, v76
	v_mul_f32_e32 v77, 0x3fb8aa3b, v77
	v_mul_f32_e32 v75, 0x3fb8aa3b, v75
	v_mul_f32_e32 v74, 0x3fb8aa3b, v74
	v_mul_f32_e32 v73, 0x3fb8aa3b, v73
	v_exp_f32_e32 v77, v77
	v_exp_f32_e32 v74, v74
	v_exp_f32_e32 v73, v73
	v_exp_f32_e32 v75, v75
	v_add_f32_e32 v196, v72, v79
	v_add_f32_e32 v236, v170, v196
	v_cvt_pk_bf16_f32 v122, v73, v74
	v_cvt_pk_bf16_f32 v123, v75, v77
	ds_read_b128 v[72:75], v220
	ds_read_b128 v[238:241], v221
	v_add_u32_e32 v121, 0x41, v171
	s_waitcnt lgkmcnt(1)
	v_mfma_f32_32x32x16_bf16 v[72:87], v[72:75], v[80:83], 0
	s_waitcnt lgkmcnt(0)
	v_mfma_f32_32x32x16_bf16 v[72:87], v[238:241], v[132:135], v[72:87]
	ds_read_b128 v[132:135], v222
	ds_read_b128 v[238:241], v223
	s_waitcnt lgkmcnt(1)
	v_mfma_f32_32x32x16_bf16 v[72:87], v[132:135], v[128:131], v[72:87]
	ds_read_b128 v[128:131], v224
	ds_read_b128 v[132:135], v225
	s_waitcnt lgkmcnt(2)
	v_mfma_f32_32x32x16_bf16 v[72:87], v[238:241], v[140:143], v[72:87]
	s_waitcnt lgkmcnt(1)
	v_mfma_f32_32x32x16_bf16 v[72:87], v[128:131], v[136:139], v[72:87]
	s_waitcnt lgkmcnt(0)
	v_mfma_f32_32x32x16_bf16 v[72:87], v[132:135], v[144:147], v[72:87]
	ds_read_b128 v[128:131], v226
	ds_read_b128 v[132:135], v227
	v_or_b32_e32 v146, 16, v159
	v_or_b32_e32 v147, 17, v159
	s_waitcnt lgkmcnt(1)
	v_mfma_f32_32x32x16_bf16 v[72:87], v[128:131], v[148:151], v[72:87]
	v_add_u32_e32 v128, 0x42, v171
	v_add_u32_e32 v129, 0x43, v171
	v_or_b32_e32 v148, 18, v159
	s_waitcnt lgkmcnt(0)
	v_mfma_f32_32x32x16_bf16 v[72:87], v[132:135], v[124:127], v[72:87]
	s_nop 11
	v_mul_f32_e32 v124, 0x3db504f3, v72
	v_mul_f32_e32 v125, 0x3db504f3, v73
	v_max_f32_e32 v130, 0, v124
	v_mul_f32_e64 v124, |v124|, s68
	v_mul_f32_e32 v126, 0x3db504f3, v74
	v_max_f32_e32 v131, 0, v125
	v_mul_f32_e64 v125, |v125|, s68
	v_exp_f32_e32 v124, v124
	v_max_f32_e32 v132, 0, v126
	v_mul_f32_e64 v126, |v126|, s68
	v_exp_f32_e32 v125, v125
	v_exp_f32_e32 v126, v126
	v_mul_f32_e32 v127, 0x3db504f3, v75
	v_max_f32_e32 v133, 0, v127
	v_mul_f32_e64 v127, |v127|, s68
	v_add_f32_e32 v124, 1.0, v124
	v_exp_f32_e32 v127, v127
	v_add_f32_e32 v125, 1.0, v125
	v_add_f32_e32 v126, 1.0, v126
	v_log_f32_e32 v124, v124
	v_add_f32_e32 v127, 1.0, v127
	v_log_f32_e32 v125, v125
	v_log_f32_e32 v126, v126
	v_mul_f32_e32 v137, 0x3f317217, v124
	v_log_f32_e32 v127, v127
	v_mul_f32_e32 v138, 0x3f317217, v125
	v_fma_f32 v137, v124, s70, -v137
	v_mul_f32_e32 v139, 0x3f317217, v126
	v_fma_f32 v138, v125, s70, -v138
	v_fmac_f32_e32 v137, 0x3377d1cf, v124
	v_fma_f32 v139, v126, s70, -v139
	v_fmac_f32_e32 v138, 0x3377d1cf, v125
	v_fmac_f32_e32 v137, 0x3f317217, v124
	v_fmac_f32_e32 v139, 0x3377d1cf, v126
	v_fmac_f32_e32 v138, 0x3f317217, v125
	v_mov_b32_e32 v124, v137
	v_mul_f32_e32 v140, 0x3f317217, v127
	v_fmac_f32_e32 v139, 0x3f317217, v126
	v_mov_b32_e32 v125, v138
	v_mov_b32_e32 v126, v139
	v_add_f32_e32 v124, v130, v124
	v_cmp_lt_i32_e64 s[6:7], v121, v154
	v_fma_f32 v121, v127, s70, -v140
	v_cmp_lt_i32_e32 vcc, v159, v154
	v_fma_f32 v72, v72, s67, -v124
	v_fmac_f32_e32 v121, 0x3377d1cf, v127
	v_add_f32_e32 v125, v131, v125
	v_add_f32_e32 v126, v132, v126
	v_cndmask_b32_e64 v130, 0, -v124, vcc
	v_cmp_lt_i32_e64 s[8:9], v128, v154
	v_cndmask_b32_e32 v72, v208, v72, vcc
	v_fmac_f32_e32 v121, 0x3f317217, v127
	v_cndmask_b32_e64 v124, 0, -v125, s[6:7]
	v_fma_f32 v73, v73, s67, -v125
	v_cndmask_b32_e64 v125, 0, -v126, s[8:9]
	v_fma_f32 v74, v74, s67, -v126
	v_mul_f32_e32 v127, 0x3db504f3, v76
	v_mul_f32_e64 v126, |v127|, s68
	v_exp_f32_e32 v128, v126
	v_cndmask_b32_e64 v73, v208, v73, s[6:7]
	v_cmp_lt_i32_e32 vcc, v129, v154
	v_max_f32_e32 v185, 0, v127
	v_add_f32_e32 v128, 1.0, v128
	v_mul_f32_e32 v127, 0x3db504f3, v77
	v_add_f32_e32 v121, v133, v121
	v_log_f32_e32 v128, v128
	v_mul_f32_e64 v129, |v127|, s68
	v_cndmask_b32_e64 v126, 0, -v121, vcc
	v_fma_f32 v75, v75, s67, -v121
	v_mul_f32_e32 v121, 0x3f317217, v128
	v_exp_f32_e32 v129, v129
	v_fma_f32 v121, v128, s70, -v121
	v_fmac_f32_e32 v121, 0x3377d1cf, v128
	v_cndmask_b32_e32 v75, v208, v75, vcc
	v_fmac_f32_e32 v121, 0x3f317217, v128
	v_max_f32_e32 v183, 0, v127
	v_mul_f32_e32 v127, 0x3db504f3, v78
	v_add_f32_e32 v128, 1.0, v129
	v_max_f32_e32 v181, 0, v127
	v_cndmask_b32_e64 v74, v208, v74, s[8:9]
	v_log_f32_e32 v128, v128
	v_mov_b32_e32 v205, v121
	v_mul_f32_e64 v129, |v127|, s68
	v_mul_f32_e32 v121, 0x3f317217, v128
	v_exp_f32_e32 v129, v129
	v_fma_f32 v121, v128, s70, -v121
	v_fmac_f32_e32 v121, 0x3377d1cf, v128
	v_fmac_f32_e32 v121, 0x3f317217, v128
	v_mul_f32_e32 v127, 0x3db504f3, v79
	v_max_f32_e32 v179, 0, v127
	v_add_f32_e32 v128, 1.0, v129
	v_or_b32_e32 v140, 9, v159
	s_nop 0
	v_log_f32_e32 v128, v128
	v_mov_b32_e32 v203, v121
	v_mul_f32_e64 v129, |v127|, s68
	v_mul_f32_e32 v121, 0x3f317217, v128
	v_exp_f32_e32 v129, v129
	v_fma_f32 v121, v128, s70, -v121
	v_fmac_f32_e32 v121, 0x3377d1cf, v128
	v_fmac_f32_e32 v121, 0x3f317217, v128
	v_mul_f32_e32 v127, 0x3db504f3, v80
	v_max_f32_e32 v177, 0, v127
	v_add_f32_e32 v128, 1.0, v129
	s_nop 1
	v_log_f32_e32 v128, v128
	v_mov_b32_e32 v201, v121
	v_mul_f32_e64 v129, |v127|, s68
	v_mul_f32_e32 v121, 0x3f317217, v128
	v_exp_f32_e32 v129, v129
	v_fma_f32 v121, v128, s70, -v121
	v_fmac_f32_e32 v121, 0x3377d1cf, v128
	v_fmac_f32_e32 v121, 0x3f317217, v128
	v_mul_f32_e32 v127, 0x3db504f3, v81
	v_max_f32_e32 v175, 0, v127
	v_add_f32_e32 v128, 1.0, v129
	s_nop 1
	v_log_f32_e32 v128, v128
	v_mov_b32_e32 v199, v121
	v_mul_f32_e64 v129, |v127|, s68
	v_mul_f32_e32 v121, 0x3f317217, v128
	v_exp_f32_e32 v129, v129
	v_fma_f32 v121, v128, s70, -v121
	v_fmac_f32_e32 v121, 0x3377d1cf, v128
	v_fmac_f32_e32 v121, 0x3f317217, v128
	v_mul_f32_e32 v127, 0x3db504f3, v82
	v_max_f32_e32 v173, 0, v127
	v_add_f32_e32 v128, 1.0, v129
	s_nop 1
	v_log_f32_e32 v128, v128
	v_mov_b32_e32 v195, v121
	v_mul_f32_e64 v129, |v127|, s68
	v_mul_f32_e32 v121, 0x3f317217, v128
	v_exp_f32_e32 v129, v129
	v_fma_f32 v121, v128, s70, -v121
	v_fmac_f32_e32 v121, 0x3377d1cf, v128
	v_fmac_f32_e32 v121, 0x3f317217, v128
	v_mul_f32_e32 v127, 0x3db504f3, v83
	v_pk_add_f32 v[134:135], v[176:177], v[194:195]
	v_add_f32_e32 v128, 1.0, v129
	s_nop 1
	v_log_f32_e32 v128, v128
	v_mov_b32_e32 v193, v121
	v_mul_f32_e64 v129, |v127|, s68
	v_mul_f32_e32 v121, 0x3f317217, v128
	v_exp_f32_e32 v129, v129
	v_fma_f32 v121, v128, s70, -v121
	v_fmac_f32_e32 v121, 0x3377d1cf, v128
	v_fmac_f32_e32 v121, 0x3f317217, v128
	v_pk_add_f32 v[136:137], v[174:175], v[192:193]
	s_nop 0
	v_add_f32_e32 v128, 1.0, v129
	s_nop 1
	v_log_f32_e32 v128, v128
	v_mov_b32_e32 v191, v121
	v_mul_f32_e32 v129, 0x3db504f3, v84
	v_mul_f32_e64 v131, |v129|, s68
	v_exp_f32_e32 v131, v131
	v_max_f32_e32 v121, 0, v127
	v_mul_f32_e32 v127, 0x3f317217, v128
	v_fma_f32 v127, v128, s70, -v127
	v_fmac_f32_e32 v127, 0x3377d1cf, v128
	v_fmac_f32_e32 v127, 0x3f317217, v128
	v_add_f32_e32 v131, 1.0, v131
	s_nop 0
	v_mov_b32_e32 v189, v127
	v_max_f32_e32 v128, 0, v129
	v_log_f32_e32 v131, v131
	v_add_u32_e32 v127, 0x58, v171
	v_pk_add_f32 v[132:133], v[178:179], v[198:199]
	v_pk_add_f32 v[138:139], v[120:121], v[188:189]
	v_mul_f32_e32 v129, 0x3f317217, v131
	v_fma_f32 v129, v131, s70, -v129
	v_fmac_f32_e32 v129, 0x3377d1cf, v131
	v_fmac_f32_e32 v129, 0x3f317217, v131
	v_or_b32_e32 v120, 19, v159
	s_nop 0
	v_add_f32_e32 v128, v128, v129
	v_mul_f32_e32 v129, 0x3db504f3, v85
	v_mul_f32_e64 v131, |v129|, s68
	v_exp_f32_e32 v131, v131
	v_cmp_lt_i32_e32 vcc, v127, v154
	v_fma_f32 v84, v84, s67, -v128
	v_add_f32_e32 v127, 1.0, v131
	v_cndmask_b32_e64 v207, 0, -v128, vcc
	v_cndmask_b32_e32 v237, v208, v84, vcc
	v_log_f32_e32 v127, v127
	v_max_f32_e32 v128, 0, v129
	v_add_u32_e32 v84, 0x59, v171
	v_mul_f32_e32 v129, 0x3f317217, v127
	v_fma_f32 v129, v127, s70, -v129
	v_fmac_f32_e32 v129, 0x3377d1cf, v127
	v_fmac_f32_e32 v129, 0x3f317217, v127
	s_nop 1
	v_mov_b32_e32 v127, v129
	v_add_f32_e32 v127, v128, v127
	v_mul_f32_e32 v128, 0x3db504f3, v86
	v_mul_f32_e64 v129, |v128|, s68
	v_exp_f32_e32 v129, v129
	v_cmp_lt_i32_e32 vcc, v84, v154
	v_fma_f32 v84, v85, s67, -v127
	v_max_f32_e32 v128, 0, v128
	v_add_f32_e32 v85, 1.0, v129
	v_cndmask_b32_e64 v187, 0, -v127, vcc
	s_nop 0
	v_log_f32_e32 v85, v85
	v_cndmask_b32_e32 v127, v208, v84, vcc
	v_add_u32_e32 v84, 0x5a, v171
	v_mul_f32_e32 v129, 0x3f317217, v85
	v_fma_f32 v129, v85, s70, -v129
	v_fmac_f32_e32 v129, 0x3377d1cf, v85
	v_fmac_f32_e32 v129, 0x3f317217, v85
	s_nop 1
	v_mov_b32_e32 v85, v129
	v_add_f32_e32 v85, v128, v85
	v_mul_f32_e32 v128, 0x3db504f3, v87
	v_mul_f32_e64 v129, |v128|, s68
	v_exp_f32_e32 v129, v129
	v_cmp_lt_i32_e32 vcc, v84, v154
	v_fma_f32 v84, v86, s67, -v85
	s_nop 0
	v_cndmask_b32_e64 v238, 0, -v85, vcc
	v_add_f32_e32 v85, 1.0, v129
	v_cndmask_b32_e32 v239, v208, v84, vcc
	v_add_u32_e32 v84, 0x5b, v171
	v_log_f32_e32 v85, v85
	v_max_f32_e32 v86, 0, v128
	v_mul_f32_e32 v128, 0x3f317217, v85
	v_fma_f32 v128, v85, s70, -v128
	v_fmac_f32_e32 v128, 0x3377d1cf, v85
	v_fmac_f32_e32 v128, 0x3f317217, v85
	s_nop 1
	v_mov_b32_e32 v85, v128
	v_add_f32_e32 v85, v86, v85
	v_cmp_lt_i32_e32 vcc, v84, v154
	v_fma_f32 v84, v87, s67, -v85
	v_or_b32_e32 v128, 32, v159
	v_cndmask_b32_e64 v240, 0, -v85, vcc
	v_cndmask_b32_e32 v241, v208, v84, vcc
	v_add_f32_e32 v84, v130, v124
	v_add_f32_e32 v85, v125, v126
	v_add_f32_e32 v84, v84, v85
	v_mov_b32_e32 v85, v84
	v_mov_b32_e32 v86, v84
	s_nop 1
	v_permlane32_swap_b32_e32 v85, v86
	v_cndmask_b32_e64 v86, v85, v86, s[4:5]
	v_add_f32_e32 v171, v84, v86
	v_cndmask_b32_e64 v242, 0, v86, s[4:5]
	v_pk_add_f32 v[86:87], v[184:185], v[204:205]
	v_cmp_lt_i32_e64 s[6:7], v128, v154
	v_fma_f32 v64, v64, s67, -v86
	v_pk_add_f32 v[128:129], v[182:183], v[202:203]
	v_cndmask_b32_e64 v184, v208, v64, s[6:7]
	v_fma_f32 v64, v65, s67, -v128
	v_or_b32_e32 v65, 33, v159
	v_cmp_lt_i32_e64 s[8:9], v65, v154
	v_pk_add_f32 v[130:131], v[180:181], v[200:201]
	v_or_b32_e32 v65, 34, v159
	v_cndmask_b32_e64 v182, v208, v64, s[8:9]
	v_fma_f32 v64, v66, s67, -v130
	v_cmp_lt_i32_e64 s[10:11], v65, v154
	v_or_b32_e32 v65, 35, v159
	v_cmp_lt_i32_e64 s[12:13], v65, v154
	v_cndmask_b32_e64 v180, v208, v64, s[10:11]
	v_fma_f32 v64, v67, s67, -v132
	v_or_b32_e32 v65, 40, v159
	v_cndmask_b32_e64 v181, v208, v64, s[12:13]
	v_fma_f32 v64, v68, s67, -v134
	v_cmp_lt_i32_e64 s[14:15], v65, v154
	v_or_b32_e32 v65, 41, v159
	v_cmp_lt_i32_e64 s[16:17], v65, v154
	v_cndmask_b32_e64 v183, v208, v64, s[14:15]
	v_fma_f32 v64, v69, s67, -v136
	v_pk_add_f32 v[68:69], v[172:173], v[190:191]
	v_or_b32_e32 v65, 42, v159
	v_cndmask_b32_e64 v185, v208, v64, s[16:17]
	v_fma_f32 v64, v70, s67, -v68
	v_cmp_lt_i32_e64 s[18:19], v65, v154
	v_or_b32_e32 v65, 43, v159
	v_or_b32_e32 v84, 8, v159
	v_or_b32_e32 v66, 10, v159
	v_or_b32_e32 v67, 11, v159
	v_cndmask_b32_e64 v190, v208, v64, s[18:19]
	v_fma_f32 v64, v71, s67, -v138
	v_cmp_lt_i32_e64 s[22:23], v65, v154
	v_cmp_lt_i32_e32 vcc, v84, v155
	v_cndmask_b32_e64 v70, 0, -v128, s[8:9]
	v_cndmask_b32_e64 v121, v208, v64, s[22:23]
	v_cndmask_b32_e64 v64, 0, -v86, s[6:7]
	v_cmp_lt_i32_e64 s[6:7], v140, v155
	v_cmp_lt_i32_e64 s[8:9], v66, v155
	v_cndmask_b32_e64 v140, 0, -v130, s[10:11]
	v_cmp_lt_i32_e64 s[10:11], v67, v155
	v_cndmask_b32_e64 v65, 0, -v87, vcc
	v_cndmask_b32_e64 v71, 0, -v129, s[6:7]
	v_cndmask_b32_e64 v141, 0, -v131, s[8:9]
	v_cndmask_b32_e64 v143, 0, -v133, s[10:11]
	v_cndmask_b32_e64 v142, 0, -v132, s[12:13]
	v_pk_add_f32 v[64:65], v[64:65], v[70:71]
	v_pk_add_f32 v[66:67], v[140:141], v[142:143]
	v_cmp_lt_i32_e64 s[12:13], v146, v155
	v_pk_add_f32 v[144:145], v[64:65], v[66:67]
	v_cndmask_b32_e64 v64, 0, -v134, s[14:15]
	v_cmp_lt_i32_e64 s[14:15], v147, v155
	v_cndmask_b32_e64 v146, 0, -v136, s[16:17]
	v_cmp_lt_i32_e64 s[16:17], v148, v155
	v_cndmask_b32_e64 v148, 0, -v68, s[18:19]
	v_cmp_lt_i32_e64 s[18:19], v120, v155
	v_cndmask_b32_e64 v65, 0, -v135, s[12:13]
	v_cndmask_b32_e64 v147, 0, -v137, s[14:15]
	v_cndmask_b32_e64 v149, 0, -v69, s[16:17]
	v_cndmask_b32_e64 v151, 0, -v139, s[18:19]
	v_cndmask_b32_e64 v150, 0, -v138, s[22:23]
	v_pk_add_f32 v[64:65], v[64:65], v[146:147]
	v_pk_add_f32 v[66:67], v[148:149], v[150:151]
	v_add_f32_e32 v85, v238, v240
	v_pk_add_f32 v[64:65], v[64:65], v[66:67]
	v_pk_add_f32 v[66:67], v[206:207], v[186:187]
	v_mov_b32_e32 v68, v64
	v_mov_b32_e32 v84, v66
	v_mov_b32_e32 v130, v66
	s_nop 1
	v_permlane32_swap_b32_e32 v84, v130
	v_mov_b32_e32 v120, v64
	v_cndmask_b32_e64 v84, v84, v130, s[4:5]
	s_nop 0
	v_permlane32_swap_b32_e32 v68, v120
	v_pk_add_f32 v[66:67], v[66:67], v[84:85]
	v_mov_b32_e32 v130, v65
	v_mov_b32_e32 v132, v65
	v_cndmask_b32_e64 v172, v68, v120, s[4:5]
	v_mov_b32_e32 v68, v67
	v_mov_b32_e32 v85, v67
	v_permlane32_swap_b32_e32 v130, v132
	s_nop 0
	v_permlane32_swap_b32_e32 v68, v85
	v_cndmask_b32_e64 v173, v130, v132, s[4:5]
	v_cndmask_b32_e64 v197, v68, v85, s[4:5]
	v_mov_b32_e32 v86, v144
	v_mov_b32_e32 v128, v144
	v_pk_add_f32 v[64:65], v[64:65], v[172:173]
	v_pk_add_f32 v[174:175], v[66:67], v[196:197]
	v_permlane32_swap_b32_e32 v86, v128
	v_pk_add_f32 v[176:177], v[64:65], v[174:175]
	v_mov_b32_e32 v65, v145
	v_mov_b32_e32 v66, v145
	s_nop 1
	v_permlane32_swap_b32_e32 v65, v66
	v_cndmask_b32_e64 v178, v86, v128, s[4:5]
	v_add_f32_e32 v64, v170, v176
	v_cndmask_b32_e64 v179, v65, v66, s[4:5]
	v_cndmask_b32_e64 v65, 0, v178, s[4:5]
	v_add_f32_e32 v64, v65, v64
	v_add_f32_e32 v65, v142, v64
	v_add_f32_e32 v64, v181, v64
	v_mul_f32_e32 v64, 0x3fb8aa3b, v64
	v_add_f32_e32 v66, v140, v65
	v_exp_f32_e32 v68, v64
	v_add_f32_e32 v64, v180, v65
	v_add_f32_e32 v67, v70, v66
	v_mul_f32_e32 v64, 0x3fb8aa3b, v64
	v_cndmask_b32_e64 v84, 0, v84, s[4:5]
	v_exp_f32_e32 v65, v64
	v_add_f32_e32 v64, v182, v66
	v_add_f32_e32 v66, v184, v67
	v_add_f32_e32 v67, v170, v174
	v_cndmask_b32_e64 v70, 0, v172, s[4:5]
	v_add_f32_e32 v84, v84, v236
	v_add_f32_e32 v67, v70, v67
	v_add_f32_e32 v120, v234, v84
	v_add_f32_e32 v70, v150, v67
	v_add_f32_e32 v67, v121, v67
	v_add_f32_e32 v121, v232, v120
	v_add_f32_e32 v120, v233, v120
	v_add_f32_e32 v85, v148, v70
	v_add_f32_e32 v70, v190, v70
	v_add_f32_e32 v128, v230, v121
	v_mul_f32_e32 v120, 0x3fb8aa3b, v120
	v_mul_f32_e32 v67, 0x3fb8aa3b, v67
	v_mul_f32_e32 v70, 0x3fb8aa3b, v70
	v_add_f32_e32 v84, v235, v84
	v_exp_f32_e32 v130, v120
	v_add_f32_e32 v120, v231, v121
	v_add_f32_e32 v121, v229, v128
	v_exp_f32_e32 v67, v67
	v_exp_f32_e32 v70, v70
	v_mul_f32_e32 v84, 0x3fb8aa3b, v84
	v_mul_f32_e32 v120, 0x3fb8aa3b, v120
	v_mul_f32_e32 v121, 0x3fb8aa3b, v121
	v_exp_f32_e32 v84, v84
	v_exp_f32_e32 v120, v120
	v_exp_f32_e32 v121, v121
	v_cvt_pk_bf16_f32 v65, v65, v68
	v_fma_f32 v68, v76, s67, -v87
	v_cvt_pk_bf16_f32 v67, v70, v67
	v_cndmask_b32_e32 v70, v208, v68, vcc
	v_fma_f32 v68, v77, s67, -v129
	v_cvt_pk_bf16_f32 v120, v121, v120
	v_cvt_pk_bf16_f32 v121, v130, v84
	v_cndmask_b32_e64 v84, v208, v68, s[6:7]
	v_fma_f32 v68, v78, s67, -v131
	v_cndmask_b32_e64 v78, v208, v68, s[8:9]
	v_fma_f32 v68, v79, s67, -v133
	v_cndmask_b32_e64 v79, v208, v68, s[10:11]
	v_fma_f32 v68, v80, s67, -v135
	v_cndmask_b32_e64 v80, v208, v68, s[12:13]
	v_fma_f32 v68, v81, s67, -v137
	v_cndmask_b32_e64 v81, v208, v68, s[14:15]
	v_fma_f32 v68, v82, s67, -v69
	v_cndmask_b32_e64 v82, v208, v68, s[16:17]
	v_fma_f32 v68, v83, s67, -v139
	v_cndmask_b32_e64 v83, v208, v68, s[18:19]
	v_pk_add_f32 v[68:69], v[144:145], v[178:179]
	v_add_f32_e32 v86, v146, v85
	v_pk_add_f32 v[68:69], v[68:69], v[176:177]
	v_add_f32_e32 v85, v185, v85
	v_add_f32_e32 v86, v183, v86
	v_pk_add_f32 v[76:77], v[170:171], v[68:69]
	v_mul_f32_e32 v64, 0x3fb8aa3b, v64
	v_mul_f32_e32 v66, 0x3fb8aa3b, v66
	v_mul_f32_e32 v85, 0x3fb8aa3b, v85
	v_mul_f32_e32 v86, 0x3fb8aa3b, v86
	v_add_f32_e32 v68, v76, v69
	v_exp_f32_e32 v64, v64
	v_exp_f32_e32 v66, v66
	v_exp_f32_e32 v85, v85
	v_exp_f32_e32 v86, v86
	v_add_f32_e32 v68, v242, v68
	v_add_f32_e32 v69, v126, v68
	v_add_f32_e32 v68, v75, v68
	v_mul_f32_e32 v68, 0x3fb8aa3b, v68
	v_exp_f32_e32 v75, v68
	v_add_f32_e32 v68, v74, v69
	v_cvt_pk_bf16_f32 v64, v66, v64
	v_cvt_pk_bf16_f32 v66, v86, v85
	v_add_f32_e32 v85, v125, v69
	v_mul_f32_e32 v68, 0x3fb8aa3b, v68
	v_exp_f32_e32 v69, v68
	v_add_f32_e32 v68, v73, v85
	v_add_f32_e32 v73, v76, v177
	v_cndmask_b32_e64 v74, 0, v179, s[4:5]
	v_add_f32_e32 v73, v74, v73
	v_add_f32_e32 v74, v143, v73
	v_add_f32_e32 v86, v124, v85
	v_add_f32_e32 v85, v141, v74
	v_add_f32_e32 v71, v71, v85
	v_add_f32_e32 v73, v79, v73
	v_add_f32_e32 v70, v70, v71
	v_add_f32_e32 v71, v76, v175
	v_cndmask_b32_e64 v79, 0, v173, s[4:5]
	v_add_f32_e32 v71, v79, v71
	v_add_f32_e32 v79, v151, v71
	v_add_f32_e32 v71, v83, v71
	v_mul_f32_e32 v71, 0x3fb8aa3b, v71
	v_exp_f32_e32 v83, v71
	v_add_f32_e32 v71, v82, v79
	v_add_f32_e32 v74, v78, v74
	v_add_f32_e32 v78, v84, v85
	v_add_f32_e32 v84, v149, v79
	v_mul_f32_e32 v71, 0x3fb8aa3b, v71
	v_exp_f32_e32 v79, v71
	v_add_f32_e32 v71, v81, v84
	v_add_f32_e32 v85, v147, v84
	v_mul_f32_e32 v71, 0x3fb8aa3b, v71
	v_exp_f32_e32 v81, v71
	v_add_f32_e32 v71, v80, v85
	v_mul_f32_e32 v71, 0x3fb8aa3b, v71
	v_exp_f32_e32 v80, v71
	v_add_f32_e32 v71, 0, v76
	v_cndmask_b32_e64 v82, 0, v197, s[4:5]
	v_add_f32_e32 v71, v71, v82
	v_add_f32_e32 v82, v240, v71
	v_add_f32_e32 v71, v71, v241
	v_mul_f32_e32 v71, 0x3fb8aa3b, v71
	v_add_f32_e32 v72, v72, v86
	v_exp_f32_e32 v86, v71
	v_add_f32_e32 v71, v239, v82
	v_add_f32_e32 v84, v238, v82
	v_mul_f32_e32 v71, 0x3fb8aa3b, v71
	v_exp_f32_e32 v82, v71
	v_add_f32_e32 v71, v127, v84
	v_add_f32_e32 v85, v187, v84
	v_mul_f32_e32 v71, 0x3fb8aa3b, v71
	v_exp_f32_e32 v84, v71
	v_add_f32_e32 v71, v237, v85
	v_mul_f32_e32 v68, 0x3fb8aa3b, v68
	v_mul_f32_e32 v72, 0x3fb8aa3b, v72
	v_mul_f32_e32 v73, 0x3fb8aa3b, v73
	v_mul_f32_e32 v74, 0x3fb8aa3b, v74
	v_mul_f32_e32 v78, 0x3fb8aa3b, v78
	v_mul_f32_e32 v70, 0x3fb8aa3b, v70
	v_mul_f32_e32 v71, 0x3fb8aa3b, v71
	v_exp_f32_e32 v68, v68
	v_exp_f32_e32 v72, v72
	v_exp_f32_e32 v73, v73
	v_exp_f32_e32 v74, v74
	v_exp_f32_e32 v78, v78
	v_exp_f32_e32 v70, v70
	v_exp_f32_e32 v85, v71
	v_add_f32_e32 v170, v76, v77
	v_cvt_pk_bf16_f32 v68, v72, v68
	v_cvt_pk_bf16_f32 v69, v69, v75
	v_cvt_pk_bf16_f32 v70, v70, v78
	v_cvt_pk_bf16_f32 v71, v74, v73
	v_cvt_pk_bf16_f32 v72, v80, v81
	v_cvt_pk_bf16_f32 v73, v79, v83
	v_cvt_pk_bf16_f32 v74, v85, v84
	v_cvt_pk_bf16_f32 v75, v82, v86
	s_or_b64 exec, exec, s[64:65]
	v_cmp_ne_u32_e32 vcc, -1, v152
	s_and_saveexec_b64 s[6:7], vcc
	s_cbranch_execz .LBB0_473
